# FFN2 gate/up epilogue: the eight row-statistic loads issued together at the epilogue start (one wait)
# speedup vs baseline: 1.0075x; 1.0037x over previous
; __device__ __forceinline__ float fsilu(float x) { return x * fsigmoid(x); }
;     __device__ __forceinline__ void operator()(const f32x4 (&acc)[2][2][4][2], const Unit& u, int wr, int wc, int fr, int fq) const {
;         const int row0 = u.pm * BM + wr * 64 + fr, col0 = u.pn * HALF + wc * 32 + 8 * fq;
; #pragma unroll
;         for (int ai = 0; ai < 2; ++ai)
; #pragma unroll
;             for (int m = 0; m < 4; ++m) { const int row = row0 + ai * HALF + m * 16;
;                 bf16_t* rowp = O + (size_t)u.pm * ((size_t)ldc * BM) + (size_t)(col0 >> 6) * (BM * 64) + (size_t)(row - u.pm * BM) * 64 + (col0 & 63);
;                 f32x4 g0 = acc[ai][0][m][0], g1 = acc[ai][0][m][1], u0 = acc[ai][1][m][0], u1 = acc[ai][1][m][1];
;                 if (RS) { const float rs = 1.0f / sqrtf(stat[row] * (1.0f / 4096.0f) + 1e-6f); g0 *= rs; g1 *= rs; u0 *= rs; u1 *= rs; }
;                 u32x4 w; w.x = pk_bf16(fsilu(g0[0]) * u0[0], fsilu(g0[1]) * u0[1]); w.y = pk_bf16(fsilu(g0[2]) * u0[2], fsilu(g0[3]) * u0[3]);
;                 w.z = pk_bf16(fsilu(g1[0]) * u1[0], fsilu(g1[1]) * u1[1]); w.w = pk_bf16(fsilu(g1[2]) * u1[2], fsilu(g1[3]) * u1[3]);
;                 *(u32x4*)rowp = w; }
.LBB0_1175:
	s_lshl_b32 s15, s4, 8
	v_add_u32_e32 v154, s15, v140
	v_ashrrev_i32_e32 v155, 31, v154
	v_lshl_add_u64 v[152:153], v[154:155], 2, s[6:7]
	global_load_dword v155, v[152:153], off
	global_load_dword v200, v[152:153], off offset:64
	global_load_dword v201, v[152:153], off offset:128
	global_load_dword v202, v[152:153], off offset:192
	global_load_dword v203, v[152:153], off offset:512
	global_load_dword v204, v[152:153], off offset:576
	global_load_dword v205, v[152:153], off offset:640
	global_load_dword v206, v[152:153], off offset:704
	v_or_b32_e32 v160, 16, v154
	v_ashrrev_i32_e32 v161, 31, v160
	s_lshl_b32 s5, s5, 7
	v_lshl_add_u64 v[162:163], v[160:161], 2, s[6:7]
	s_mul_hi_i32 s17, s4, 0x560000
	s_mul_i32 s22, s4, 0x560000
	s_or_b32 s4, s5, s44
	s_ashr_i32 s4, s4, 6
	s_ashr_i32 s5, s4, 31
	s_lshl_b64 s[4:5], s[4:5], 15
	s_add_u32 s22, s52, s22
	s_addc_u32 s17, s53, s17
	s_add_u32 s22, s22, s4
	s_addc_u32 s23, s17, s5
	v_lshl_add_u64 v[164:165], s[22:23], 0, v[142:143]
	v_lshl_add_u64 v[164:165], v[164:165], 0, v[138:139]
	s_waitcnt vmcnt(0)
	v_fmamk_f32 v155, v155, 0x39800000, v158
	v_mul_f32_e32 v161, 0x4f800000, v155
	v_cmp_gt_f32_e32 vcc, s57, v155
	s_nop 1
	v_cndmask_b32_e32 v155, v155, v161, vcc
	v_sqrt_f32_e32 v161, v155
	s_nop 0
	v_add_u32_e32 v166, -1, v161
	v_add_u32_e32 v167, 1, v161
	v_fma_f32 v168, -v166, v161, v155
	v_fma_f32 v169, -v167, v161, v155
	v_cmp_ge_f32_e64 s[4:5], 0, v168
	s_nop 1
	v_cndmask_b32_e64 v161, v161, v166, s[4:5]
	v_cmp_lt_f32_e64 s[4:5], 0, v169
	s_nop 1
	v_cndmask_b32_e64 v161, v161, v167, s[4:5]
	v_mul_f32_e32 v166, 0x37800000, v161
	v_cndmask_b32_e32 v161, v161, v166, vcc
	v_cmp_class_f32_e32 vcc, v155, v159
	s_nop 1
	v_cndmask_b32_e32 v155, v161, v155, vcc
	v_div_scale_f32 v161, s[4:5], v155, v155, 1.0
	v_rcp_f32_e32 v166, v161
	v_div_scale_f32 v167, vcc, 1.0, v155, 1.0
	v_fma_f32 v168, -v161, v166, 1.0
	v_fmac_f32_e32 v166, v168, v166
	v_mul_f32_e32 v168, v167, v166
	v_fma_f32 v169, -v161, v168, v167
	v_fmac_f32_e32 v168, v169, v166
	v_fma_f32 v161, -v161, v168, v167
	v_div_fmas_f32 v161, v161, v166, v168
	v_div_fixup_f32 v166, v161, v155, 1.0
	v_pk_mul_f32 v[128:129], v[128:129], v[166:167] op_sel_hi:[1,0]
	v_pk_mul_f32 v[126:127], v[126:127], v[166:167] op_sel_hi:[1,0]
	v_pk_mul_f32 v[124:125], v[124:125], v[166:167] op_sel_hi:[1,0]
	v_pk_mul_f32 v[122:123], v[122:123], v[166:167] op_sel_hi:[1,0]
	v_pk_mul_f32 v[120:121], v[120:121], v[166:167] op_sel_hi:[1,0]
	v_pk_mul_f32 v[118:119], v[118:119], v[166:167] op_sel_hi:[1,0]
	v_pk_mul_f32 v[116:117], v[116:117], v[166:167] op_sel_hi:[1,0]
	v_pk_mul_f32 v[114:115], v[114:115], v[166:167] op_sel_hi:[1,0]
	v_mul_f32_e32 v155, 0xbfb8aa3b, v126
	v_mul_f32_e32 v161, 0xbfb8aa3b, v127
	v_mul_f32_e32 v166, 0xbfb8aa3b, v128
	v_mul_f32_e32 v167, 0xbfb8aa3b, v129
	v_mul_f32_e32 v168, 0xbfb8aa3b, v122
	v_mul_f32_e32 v169, 0xbfb8aa3b, v123
	v_mul_f32_e32 v170, 0xbfb8aa3b, v124
	v_mul_f32_e32 v171, 0xbfb8aa3b, v125
	v_exp_f32_e32 v155, v155
	v_exp_f32_e32 v161, v161
	v_exp_f32_e32 v166, v166
	v_exp_f32_e32 v167, v167
	v_exp_f32_e32 v168, v168
	v_exp_f32_e32 v169, v169
	v_exp_f32_e32 v170, v170
	v_exp_f32_e32 v171, v171
	v_add_f32_e32 v155, 1.0, v155
	v_add_f32_e32 v161, 1.0, v161
	v_add_f32_e32 v172, 1.0, v166
	v_add_f32_e32 v173, 1.0, v167
	v_add_f32_e32 v174, 1.0, v168
	v_add_f32_e32 v175, 1.0, v169
	v_add_f32_e32 v176, 1.0, v170
	v_add_f32_e32 v177, 1.0, v171
	v_rcp_f32_e32 v166, v155
	v_rcp_f32_e32 v167, v161
	v_rcp_f32_e32 v168, v172
	v_rcp_f32_e32 v169, v173
	v_rcp_f32_e32 v170, v174
	v_rcp_f32_e32 v171, v175
	v_rcp_f32_e32 v172, v176
	v_rcp_f32_e32 v173, v177
	v_pk_mul_f32 v[126:127], v[126:127], v[166:167]
	v_pk_mul_f32 v[128:129], v[128:129], v[168:169]
	v_pk_mul_f32 v[122:123], v[122:123], v[170:171]
	v_pk_mul_f32 v[124:125], v[124:125], v[172:173]
	v_pk_mul_f32 v[118:119], v[118:119], v[126:127]
	v_pk_mul_f32 v[120:121], v[120:121], v[128:129]
	v_pk_mul_f32 v[122:123], v[114:115], v[122:123]
	v_pk_mul_f32 v[124:125], v[116:117], v[124:125]
	v_cvt_pk_bf16_f32 v114, v118, v119
	v_cvt_pk_bf16_f32 v115, v120, v121
	v_cvt_pk_bf16_f32 v116, v122, v123
	v_cvt_pk_bf16_f32 v117, v124, v125
	global_store_dwordx4 v[164:165], v[114:117], off
	s_nop 1
	v_mov_b32_e32 v118, v200
	v_fmamk_f32 v118, v118, 0x39800000, v158
	v_mul_f32_e32 v119, 0x4f800000, v118
	v_cmp_gt_f32_e32 vcc, s57, v118
	v_or_b32_e32 v114, 32, v154
	v_ashrrev_i32_e32 v115, 31, v114
	v_cndmask_b32_e32 v120, v118, v119, vcc
	v_sqrt_f32_e32 v121, v120
	v_lshl_add_u64 v[118:119], v[114:115], 2, s[6:7]
	v_subrev_u32_e32 v116, s15, v160
	v_ashrrev_i32_e32 v117, 31, v116
	v_add_u32_e32 v115, -1, v121
	v_add_u32_e32 v122, 1, v121
	v_fma_f32 v123, -v115, v121, v120
	v_fma_f32 v124, -v122, v121, v120
	v_cmp_ge_f32_e64 s[4:5], 0, v123
	v_lshlrev_b64 v[116:117], 7, v[116:117]
	v_lshl_add_u64 v[116:117], s[22:23], 0, v[116:117]
	v_cndmask_b32_e64 v115, v121, v115, s[4:5]
	v_cmp_lt_f32_e64 s[4:5], 0, v124
	v_lshl_add_u64 v[116:117], v[116:117], 0, v[138:139]
	s_nop 0
	v_cndmask_b32_e64 v115, v115, v122, s[4:5]
	v_mul_f32_e32 v121, 0x37800000, v115
	v_cndmask_b32_e32 v115, v115, v121, vcc
	v_cmp_class_f32_e32 vcc, v120, v159
	s_nop 1
	v_cndmask_b32_e32 v115, v115, v120, vcc
	v_div_scale_f32 v120, s[4:5], v115, v115, 1.0
	v_rcp_f32_e32 v121, v120
	v_div_scale_f32 v122, vcc, 1.0, v115, 1.0
	v_fma_f32 v123, -v120, v121, 1.0
	v_fmac_f32_e32 v121, v123, v121
	v_mul_f32_e32 v123, v122, v121
	v_fma_f32 v124, -v120, v123, v122
	v_fmac_f32_e32 v123, v124, v121
	v_fma_f32 v120, -v120, v123, v122
	v_div_fmas_f32 v120, v120, v121, v123
	v_div_fixup_f32 v120, v120, v115, 1.0
; __device__ __forceinline__ float fsilu(float x) { return x * fsigmoid(x); }
;     __device__ __forceinline__ void operator()(const f32x4 (&acc)[2][2][4][2], const Unit& u, int wr, int wc, int fr, int fq) const {
;     ...
;             for (int m = 0; m < 4; ++m) { const int row = row0 + ai * HALF + m * 16;
;                 bf16_t* rowp = O + (size_t)u.pm * ((size_t)ldc * BM) + (size_t)(col0 >> 6) * (BM * 64) + (size_t)(row - u.pm * BM) * 64 + (col0 & 63);
;                 f32x4 g0 = acc[ai][0][m][0], g1 = acc[ai][0][m][1], u0 = acc[ai][1][m][0], u1 = acc[ai][1][m][1];
;                 if (RS) { const float rs = 1.0f / sqrtf(stat[row] * (1.0f / 4096.0f) + 1e-6f); g0 *= rs; g1 *= rs; u0 *= rs; u1 *= rs; }
;                 u32x4 w; w.x = pk_bf16(fsilu(g0[0]) * u0[0], fsilu(g0[1]) * u0[1]); w.y = pk_bf16(fsilu(g0[2]) * u0[2], fsilu(g0[3]) * u0[3]);
;                 w.z = pk_bf16(fsilu(g1[0]) * u1[0], fsilu(g1[1]) * u1[1]); w.w = pk_bf16(fsilu(g1[2]) * u1[2], fsilu(g1[3]) * u1[3]);
;                 *(u32x4*)rowp = w; }
	v_pk_mul_f32 v[112:113], v[112:113], v[120:121] op_sel_hi:[1,0]
	v_pk_mul_f32 v[110:111], v[110:111], v[120:121] op_sel_hi:[1,0]
	v_pk_mul_f32 v[108:109], v[108:109], v[120:121] op_sel_hi:[1,0]
	v_pk_mul_f32 v[106:107], v[106:107], v[120:121] op_sel_hi:[1,0]
	v_pk_mul_f32 v[104:105], v[104:105], v[120:121] op_sel_hi:[1,0]
	v_pk_mul_f32 v[102:103], v[102:103], v[120:121] op_sel_hi:[1,0]
	v_pk_mul_f32 v[100:101], v[100:101], v[120:121] op_sel_hi:[1,0]
	v_pk_mul_f32 v[98:99], v[98:99], v[120:121] op_sel_hi:[1,0]
	v_mul_f32_e32 v115, 0xbfb8aa3b, v110
	v_mul_f32_e32 v120, 0xbfb8aa3b, v111
	v_mul_f32_e32 v121, 0xbfb8aa3b, v112
	v_mul_f32_e32 v122, 0xbfb8aa3b, v113
	v_mul_f32_e32 v123, 0xbfb8aa3b, v106
	v_mul_f32_e32 v124, 0xbfb8aa3b, v107
	v_mul_f32_e32 v125, 0xbfb8aa3b, v108
	v_mul_f32_e32 v126, 0xbfb8aa3b, v109
	v_exp_f32_e32 v115, v115
	v_exp_f32_e32 v120, v120
	v_exp_f32_e32 v121, v121
	v_exp_f32_e32 v122, v122
	v_exp_f32_e32 v123, v123
	v_exp_f32_e32 v124, v124
	v_exp_f32_e32 v125, v125
	v_exp_f32_e32 v126, v126
	v_add_f32_e32 v115, 1.0, v115
	v_add_f32_e32 v127, 1.0, v120
	v_add_f32_e32 v128, 1.0, v121
	v_add_f32_e32 v129, 1.0, v122
	v_add_f32_e32 v155, 1.0, v123
	v_add_f32_e32 v160, 1.0, v124
	v_add_f32_e32 v161, 1.0, v125
	v_add_f32_e32 v162, 1.0, v126
	v_rcp_f32_e32 v120, v115
	v_rcp_f32_e32 v121, v127
	v_rcp_f32_e32 v122, v128
	v_rcp_f32_e32 v123, v129
	v_rcp_f32_e32 v124, v155
	v_rcp_f32_e32 v125, v160
	v_rcp_f32_e32 v126, v161
	v_rcp_f32_e32 v127, v162
	v_pk_mul_f32 v[110:111], v[110:111], v[120:121]
	v_pk_mul_f32 v[112:113], v[112:113], v[122:123]
	v_pk_mul_f32 v[106:107], v[106:107], v[124:125]
	v_pk_mul_f32 v[108:109], v[108:109], v[126:127]
	v_pk_mul_f32 v[102:103], v[102:103], v[110:111]
	v_pk_mul_f32 v[104:105], v[104:105], v[112:113]
	v_pk_mul_f32 v[106:107], v[98:99], v[106:107]
	v_pk_mul_f32 v[108:109], v[100:101], v[108:109]
	v_cvt_pk_bf16_f32 v98, v102, v103
	v_cvt_pk_bf16_f32 v99, v104, v105
	v_cvt_pk_bf16_f32 v100, v106, v107
	v_cvt_pk_bf16_f32 v101, v108, v109
	global_store_dwordx4 v[116:117], v[98:101], off
	s_nop 1
	v_mov_b32_e32 v102, v201
	v_fmamk_f32 v102, v102, 0x39800000, v158
	v_mul_f32_e32 v103, 0x4f800000, v102
	v_cmp_gt_f32_e32 vcc, s57, v102
	v_or_b32_e32 v98, 48, v154
	v_ashrrev_i32_e32 v99, 31, v98
	v_cndmask_b32_e32 v104, v102, v103, vcc
	v_sqrt_f32_e32 v105, v104
	v_lshl_add_u64 v[102:103], v[98:99], 2, s[6:7]
	v_subrev_u32_e32 v100, s15, v114
	v_ashrrev_i32_e32 v101, 31, v100
	v_add_u32_e32 v99, -1, v105
	v_add_u32_e32 v106, 1, v105
	v_fma_f32 v107, -v99, v105, v104
	v_fma_f32 v108, -v106, v105, v104
	v_cmp_ge_f32_e64 s[4:5], 0, v107
	v_lshlrev_b64 v[100:101], 7, v[100:101]
	v_lshl_add_u64 v[100:101], s[22:23], 0, v[100:101]
	v_cndmask_b32_e64 v99, v105, v99, s[4:5]
	v_cmp_lt_f32_e64 s[4:5], 0, v108
	v_lshl_add_u64 v[100:101], v[100:101], 0, v[138:139]
	s_nop 0
	v_cndmask_b32_e64 v99, v99, v106, s[4:5]
	v_mul_f32_e32 v105, 0x37800000, v99
	v_cndmask_b32_e32 v99, v99, v105, vcc
	v_cmp_class_f32_e32 vcc, v104, v159
	s_nop 1
	v_cndmask_b32_e32 v99, v99, v104, vcc
	v_div_scale_f32 v104, s[4:5], v99, v99, 1.0
	v_rcp_f32_e32 v105, v104
	v_div_scale_f32 v106, vcc, 1.0, v99, 1.0
	v_fma_f32 v107, -v104, v105, 1.0
	v_fmac_f32_e32 v105, v107, v105
	v_mul_f32_e32 v107, v106, v105
	v_fma_f32 v108, -v104, v107, v106
	v_fmac_f32_e32 v107, v108, v105
	v_fma_f32 v104, -v104, v107, v106
	v_div_fmas_f32 v104, v104, v105, v107
	v_div_fixup_f32 v104, v104, v99, 1.0
	v_pk_mul_f32 v[96:97], v[96:97], v[104:105] op_sel_hi:[1,0]
	v_pk_mul_f32 v[94:95], v[94:95], v[104:105] op_sel_hi:[1,0]
	v_pk_mul_f32 v[92:93], v[92:93], v[104:105] op_sel_hi:[1,0]
	v_pk_mul_f32 v[90:91], v[90:91], v[104:105] op_sel_hi:[1,0]
	v_pk_mul_f32 v[88:89], v[88:89], v[104:105] op_sel_hi:[1,0]
	v_pk_mul_f32 v[86:87], v[86:87], v[104:105] op_sel_hi:[1,0]
	v_pk_mul_f32 v[84:85], v[84:85], v[104:105] op_sel_hi:[1,0]
	v_pk_mul_f32 v[82:83], v[82:83], v[104:105] op_sel_hi:[1,0]
	v_mul_f32_e32 v99, 0xbfb8aa3b, v94
	v_mul_f32_e32 v104, 0xbfb8aa3b, v95
	v_mul_f32_e32 v105, 0xbfb8aa3b, v96
	v_mul_f32_e32 v106, 0xbfb8aa3b, v97
	v_mul_f32_e32 v107, 0xbfb8aa3b, v90
	v_mul_f32_e32 v108, 0xbfb8aa3b, v91
	v_mul_f32_e32 v109, 0xbfb8aa3b, v92
	v_mul_f32_e32 v110, 0xbfb8aa3b, v93
	v_exp_f32_e32 v99, v99
	v_exp_f32_e32 v104, v104
	v_exp_f32_e32 v105, v105
	v_exp_f32_e32 v106, v106
	v_exp_f32_e32 v107, v107
	v_exp_f32_e32 v108, v108
	v_exp_f32_e32 v109, v109
	v_exp_f32_e32 v110, v110
	v_add_f32_e32 v99, 1.0, v99
	v_add_f32_e32 v111, 1.0, v104
	v_add_f32_e32 v112, 1.0, v105
	v_add_f32_e32 v113, 1.0, v106
	v_add_f32_e32 v114, 1.0, v107
	v_add_f32_e32 v115, 1.0, v108
	v_add_f32_e32 v116, 1.0, v109
	v_add_f32_e32 v117, 1.0, v110
	v_rcp_f32_e32 v104, v99
	v_rcp_f32_e32 v105, v111
	v_rcp_f32_e32 v106, v112
	v_rcp_f32_e32 v107, v113
	v_rcp_f32_e32 v108, v114
	v_rcp_f32_e32 v109, v115
	v_rcp_f32_e32 v110, v116
	v_rcp_f32_e32 v111, v117
	v_pk_mul_f32 v[94:95], v[94:95], v[104:105]
	v_pk_mul_f32 v[96:97], v[96:97], v[106:107]
	v_pk_mul_f32 v[90:91], v[90:91], v[108:109]
	v_pk_mul_f32 v[92:93], v[92:93], v[110:111]
	v_pk_mul_f32 v[86:87], v[86:87], v[94:95]
	v_pk_mul_f32 v[88:89], v[88:89], v[96:97]
	v_pk_mul_f32 v[90:91], v[82:83], v[90:91]
	v_pk_mul_f32 v[92:93], v[84:85], v[92:93]
	v_cvt_pk_bf16_f32 v82, v86, v87
	v_cvt_pk_bf16_f32 v83, v88, v89
	v_cvt_pk_bf16_f32 v84, v90, v91
	v_cvt_pk_bf16_f32 v85, v92, v93
	global_store_dwordx4 v[100:101], v[82:85], off
	s_nop 1
	s_nop 0
	v_subrev_u32_e32 v82, s15, v98
	v_mov_b32_e32 v83, v202
	v_fmamk_f32 v83, v83, 0x39800000, v158
	v_mul_f32_e32 v84, 0x4f800000, v83
	v_cmp_gt_f32_e32 vcc, s57, v83
	s_nop 1
	v_cndmask_b32_e32 v84, v83, v84, vcc
; __device__ __forceinline__ float fsilu(float x) { return x * fsigmoid(x); }
;     __device__ __forceinline__ void operator()(const f32x4 (&acc)[2][2][4][2], const Unit& u, int wr, int wc, int fr, int fq) const {
;     ...
;             for (int m = 0; m < 4; ++m) { const int row = row0 + ai * HALF + m * 16;
;                 bf16_t* rowp = O + (size_t)u.pm * ((size_t)ldc * BM) + (size_t)(col0 >> 6) * (BM * 64) + (size_t)(row - u.pm * BM) * 64 + (col0 & 63);
;                 f32x4 g0 = acc[ai][0][m][0], g1 = acc[ai][0][m][1], u0 = acc[ai][1][m][0], u1 = acc[ai][1][m][1];
;                 if (RS) { const float rs = 1.0f / sqrtf(stat[row] * (1.0f / 4096.0f) + 1e-6f); g0 *= rs; g1 *= rs; u0 *= rs; u1 *= rs; }
;                 u32x4 w; w.x = pk_bf16(fsilu(g0[0]) * u0[0], fsilu(g0[1]) * u0[1]); w.y = pk_bf16(fsilu(g0[2]) * u0[2], fsilu(g0[3]) * u0[3]);
;                 w.z = pk_bf16(fsilu(g1[0]) * u1[0], fsilu(g1[1]) * u1[1]); w.w = pk_bf16(fsilu(g1[2]) * u1[2], fsilu(g1[3]) * u1[3]);
;                 *(u32x4*)rowp = w; }
	v_sqrt_f32_e32 v85, v84
	v_ashrrev_i32_e32 v83, 31, v82
	v_lshlrev_b64 v[82:83], 7, v[82:83]
	v_lshl_add_u64 v[82:83], s[22:23], 0, v[82:83]
	v_add_u32_e32 v86, -1, v85
	v_add_u32_e32 v87, 1, v85
	v_fma_f32 v88, -v86, v85, v84
	v_fma_f32 v89, -v87, v85, v84
	v_cmp_ge_f32_e64 s[4:5], 0, v88
	v_lshl_add_u64 v[82:83], v[82:83], 0, v[138:139]
	s_nop 0
	v_cndmask_b32_e64 v85, v85, v86, s[4:5]
	v_cmp_lt_f32_e64 s[4:5], 0, v89
	s_nop 1
	v_cndmask_b32_e64 v85, v85, v87, s[4:5]
	v_mul_f32_e32 v86, 0x37800000, v85
	v_cndmask_b32_e32 v85, v85, v86, vcc
	v_cmp_class_f32_e32 vcc, v84, v159
	s_nop 1
	v_cndmask_b32_e32 v84, v85, v84, vcc
	v_div_scale_f32 v85, s[4:5], v84, v84, 1.0
	v_rcp_f32_e32 v86, v85
	v_div_scale_f32 v87, vcc, 1.0, v84, 1.0
	v_fma_f32 v88, -v85, v86, 1.0
	v_fmac_f32_e32 v86, v88, v86
	v_mul_f32_e32 v88, v87, v86
	v_fma_f32 v89, -v85, v88, v87
	v_fmac_f32_e32 v88, v89, v86
	v_fma_f32 v85, -v85, v88, v87
	v_div_fmas_f32 v85, v85, v86, v88
	v_div_fixup_f32 v84, v85, v84, 1.0
	v_pk_mul_f32 v[80:81], v[80:81], v[84:85] op_sel_hi:[1,0]
	v_pk_mul_f32 v[78:79], v[78:79], v[84:85] op_sel_hi:[1,0]
	v_pk_mul_f32 v[76:77], v[76:77], v[84:85] op_sel_hi:[1,0]
	v_pk_mul_f32 v[74:75], v[74:75], v[84:85] op_sel_hi:[1,0]
	v_pk_mul_f32 v[72:73], v[72:73], v[84:85] op_sel_hi:[1,0]
	v_pk_mul_f32 v[70:71], v[70:71], v[84:85] op_sel_hi:[1,0]
	v_pk_mul_f32 v[68:69], v[68:69], v[84:85] op_sel_hi:[1,0]
	v_pk_mul_f32 v[66:67], v[66:67], v[84:85] op_sel_hi:[1,0]
	v_mul_f32_e32 v84, 0xbfb8aa3b, v78
	v_mul_f32_e32 v85, 0xbfb8aa3b, v79
	v_mul_f32_e32 v86, 0xbfb8aa3b, v80
	v_mul_f32_e32 v87, 0xbfb8aa3b, v81
	v_mul_f32_e32 v88, 0xbfb8aa3b, v74
	v_mul_f32_e32 v89, 0xbfb8aa3b, v75
	v_mul_f32_e32 v90, 0xbfb8aa3b, v76
	v_mul_f32_e32 v91, 0xbfb8aa3b, v77
	v_exp_f32_e32 v84, v84
	v_exp_f32_e32 v85, v85
	v_exp_f32_e32 v86, v86
	v_exp_f32_e32 v87, v87
	v_exp_f32_e32 v88, v88
	v_exp_f32_e32 v89, v89
	v_exp_f32_e32 v90, v90
	v_exp_f32_e32 v91, v91
	v_add_f32_e32 v84, 1.0, v84
	v_add_f32_e32 v85, 1.0, v85
	v_add_f32_e32 v86, 1.0, v86
	v_add_f32_e32 v87, 1.0, v87
	v_add_f32_e32 v88, 1.0, v88
	v_add_f32_e32 v89, 1.0, v89
	v_add_f32_e32 v90, 1.0, v90
	v_add_f32_e32 v91, 1.0, v91
	v_rcp_f32_e32 v84, v84
	v_rcp_f32_e32 v85, v85
	v_rcp_f32_e32 v86, v86
	v_rcp_f32_e32 v87, v87
	v_rcp_f32_e32 v88, v88
	v_rcp_f32_e32 v89, v89
	v_rcp_f32_e32 v90, v90
	v_rcp_f32_e32 v91, v91
	v_pk_mul_f32 v[78:79], v[78:79], v[84:85]
	v_pk_mul_f32 v[80:81], v[80:81], v[86:87]
	v_pk_mul_f32 v[74:75], v[74:75], v[88:89]
	v_pk_mul_f32 v[76:77], v[76:77], v[90:91]
	v_pk_mul_f32 v[70:71], v[70:71], v[78:79]
	v_pk_mul_f32 v[72:73], v[72:73], v[80:81]
	v_pk_mul_f32 v[74:75], v[66:67], v[74:75]
	v_pk_mul_f32 v[76:77], v[68:69], v[76:77]
	v_cvt_pk_bf16_f32 v66, v70, v71
	v_cvt_pk_bf16_f32 v67, v72, v73
	v_cvt_pk_bf16_f32 v68, v74, v75
	v_cvt_pk_bf16_f32 v69, v76, v77
	global_store_dwordx4 v[82:83], v[66:69], off
	s_nop 1
	s_nop 0
	v_add_u32_e32 v66, 0x80, v140
	v_mov_b32_e32 v67, v203
	v_fmamk_f32 v67, v67, 0x39800000, v158
	v_mul_f32_e32 v68, 0x4f800000, v67
	v_cmp_gt_f32_e32 vcc, s57, v67
	s_nop 1
	v_cndmask_b32_e32 v68, v67, v68, vcc
	v_sqrt_f32_e32 v69, v68
	v_mov_b32_e32 v67, v139
	v_lshlrev_b64 v[66:67], 7, v[66:67]
	v_lshl_add_u64 v[66:67], s[22:23], 0, v[66:67]
	v_add_u32_e32 v70, -1, v69
	v_add_u32_e32 v71, 1, v69
	v_fma_f32 v72, -v70, v69, v68
	v_fma_f32 v73, -v71, v69, v68
	v_cmp_ge_f32_e64 s[4:5], 0, v72
	v_lshl_add_u64 v[66:67], v[66:67], 0, v[138:139]
	s_nop 0
	v_cndmask_b32_e64 v69, v69, v70, s[4:5]
	v_cmp_lt_f32_e64 s[4:5], 0, v73
	s_nop 1
	v_cndmask_b32_e64 v69, v69, v71, s[4:5]
	v_mul_f32_e32 v70, 0x37800000, v69
	v_cndmask_b32_e32 v69, v69, v70, vcc
	v_cmp_class_f32_e32 vcc, v68, v159
	s_nop 1
	v_cndmask_b32_e32 v68, v69, v68, vcc
	v_div_scale_f32 v69, s[4:5], v68, v68, 1.0
	v_rcp_f32_e32 v70, v69
	v_div_scale_f32 v71, vcc, 1.0, v68, 1.0
	v_fma_f32 v72, -v69, v70, 1.0
	v_fmac_f32_e32 v70, v72, v70
	v_mul_f32_e32 v72, v71, v70
	v_fma_f32 v73, -v69, v72, v71
	v_fmac_f32_e32 v72, v73, v70
	v_fma_f32 v69, -v69, v72, v71
	v_div_fmas_f32 v69, v69, v70, v72
	v_div_fixup_f32 v68, v69, v68, 1.0
	v_pk_mul_f32 v[64:65], v[64:65], v[68:69] op_sel_hi:[1,0]
	v_pk_mul_f32 v[62:63], v[62:63], v[68:69] op_sel_hi:[1,0]
	v_pk_mul_f32 v[60:61], v[60:61], v[68:69] op_sel_hi:[1,0]
	v_pk_mul_f32 v[58:59], v[58:59], v[68:69] op_sel_hi:[1,0]
	v_pk_mul_f32 v[56:57], v[56:57], v[68:69] op_sel_hi:[1,0]
	v_pk_mul_f32 v[54:55], v[54:55], v[68:69] op_sel_hi:[1,0]
	v_pk_mul_f32 v[52:53], v[52:53], v[68:69] op_sel_hi:[1,0]
	v_pk_mul_f32 v[50:51], v[50:51], v[68:69] op_sel_hi:[1,0]
	v_mul_f32_e32 v68, 0xbfb8aa3b, v62
	v_mul_f32_e32 v69, 0xbfb8aa3b, v63
	v_mul_f32_e32 v70, 0xbfb8aa3b, v64
	v_mul_f32_e32 v71, 0xbfb8aa3b, v65
	v_mul_f32_e32 v72, 0xbfb8aa3b, v58
	v_mul_f32_e32 v73, 0xbfb8aa3b, v59
	v_mul_f32_e32 v74, 0xbfb8aa3b, v60
	v_mul_f32_e32 v75, 0xbfb8aa3b, v61
	v_exp_f32_e32 v68, v68
	v_exp_f32_e32 v69, v69
	v_exp_f32_e32 v70, v70
	v_exp_f32_e32 v71, v71
	v_exp_f32_e32 v72, v72
	v_exp_f32_e32 v73, v73
	v_exp_f32_e32 v74, v74
	v_exp_f32_e32 v75, v75
	v_add_f32_e32 v68, 1.0, v68
	v_add_f32_e32 v69, 1.0, v69
	v_add_f32_e32 v70, 1.0, v70
	v_add_f32_e32 v71, 1.0, v71
	v_add_f32_e32 v72, 1.0, v72
	v_add_f32_e32 v73, 1.0, v73
	v_add_f32_e32 v74, 1.0, v74
	v_add_f32_e32 v75, 1.0, v75
	v_rcp_f32_e32 v68, v68
	v_rcp_f32_e32 v69, v69
	v_rcp_f32_e32 v70, v70
	v_rcp_f32_e32 v71, v71
	v_rcp_f32_e32 v72, v72
	v_rcp_f32_e32 v73, v73
	v_rcp_f32_e32 v74, v74
	v_rcp_f32_e32 v75, v75
	v_pk_mul_f32 v[62:63], v[62:63], v[68:69]
	v_pk_mul_f32 v[64:65], v[64:65], v[70:71]
	v_pk_mul_f32 v[58:59], v[58:59], v[72:73]
	v_pk_mul_f32 v[60:61], v[60:61], v[74:75]
; __device__ __forceinline__ float fsilu(float x) { return x * fsigmoid(x); }
;     __device__ __forceinline__ void operator()(const f32x4 (&acc)[2][2][4][2], const Unit& u, int wr, int wc, int fr, int fq) const {
;     ...
;             for (int m = 0; m < 4; ++m) { const int row = row0 + ai * HALF + m * 16;
;                 bf16_t* rowp = O + (size_t)u.pm * ((size_t)ldc * BM) + (size_t)(col0 >> 6) * (BM * 64) + (size_t)(row - u.pm * BM) * 64 + (col0 & 63);
;                 f32x4 g0 = acc[ai][0][m][0], g1 = acc[ai][0][m][1], u0 = acc[ai][1][m][0], u1 = acc[ai][1][m][1];
;                 if (RS) { const float rs = 1.0f / sqrtf(stat[row] * (1.0f / 4096.0f) + 1e-6f); g0 *= rs; g1 *= rs; u0 *= rs; u1 *= rs; }
;                 u32x4 w; w.x = pk_bf16(fsilu(g0[0]) * u0[0], fsilu(g0[1]) * u0[1]); w.y = pk_bf16(fsilu(g0[2]) * u0[2], fsilu(g0[3]) * u0[3]);
;                 w.z = pk_bf16(fsilu(g1[0]) * u1[0], fsilu(g1[1]) * u1[1]); w.w = pk_bf16(fsilu(g1[2]) * u1[2], fsilu(g1[3]) * u1[3]);
;                 *(u32x4*)rowp = w; }
	v_pk_mul_f32 v[54:55], v[54:55], v[62:63]
	v_pk_mul_f32 v[56:57], v[56:57], v[64:65]
	v_pk_mul_f32 v[58:59], v[50:51], v[58:59]
	v_pk_mul_f32 v[60:61], v[52:53], v[60:61]
	v_cvt_pk_bf16_f32 v50, v54, v55
	v_cvt_pk_bf16_f32 v51, v56, v57
	v_cvt_pk_bf16_f32 v52, v58, v59
	v_cvt_pk_bf16_f32 v53, v60, v61
	global_store_dwordx4 v[66:67], v[50:53], off
	s_nop 1
	s_nop 0
	v_add_u32_e32 v50, 0x90, v140
	v_mov_b32_e32 v51, v204
	v_fmamk_f32 v51, v51, 0x39800000, v158
	v_mul_f32_e32 v52, 0x4f800000, v51
	v_cmp_gt_f32_e32 vcc, s57, v51
	s_nop 1
	v_cndmask_b32_e32 v52, v51, v52, vcc
	v_sqrt_f32_e32 v53, v52
	v_mov_b32_e32 v51, v139
	v_lshlrev_b64 v[50:51], 7, v[50:51]
	v_lshl_add_u64 v[50:51], s[22:23], 0, v[50:51]
	v_add_u32_e32 v54, -1, v53
	v_add_u32_e32 v55, 1, v53
	v_fma_f32 v56, -v54, v53, v52
	v_fma_f32 v57, -v55, v53, v52
	v_cmp_ge_f32_e64 s[4:5], 0, v56
	v_lshl_add_u64 v[50:51], v[50:51], 0, v[138:139]
	s_nop 0
	v_cndmask_b32_e64 v53, v53, v54, s[4:5]
	v_cmp_lt_f32_e64 s[4:5], 0, v57
	s_nop 1
	v_cndmask_b32_e64 v53, v53, v55, s[4:5]
	v_mul_f32_e32 v54, 0x37800000, v53
	v_cndmask_b32_e32 v53, v53, v54, vcc
	v_cmp_class_f32_e32 vcc, v52, v159
	s_nop 1
	v_cndmask_b32_e32 v52, v53, v52, vcc
	v_div_scale_f32 v53, s[4:5], v52, v52, 1.0
	v_rcp_f32_e32 v54, v53
	v_div_scale_f32 v55, vcc, 1.0, v52, 1.0
	v_fma_f32 v56, -v53, v54, 1.0
	v_fmac_f32_e32 v54, v56, v54
	v_mul_f32_e32 v56, v55, v54
	v_fma_f32 v57, -v53, v56, v55
	v_fmac_f32_e32 v56, v57, v54
	v_fma_f32 v53, -v53, v56, v55
	v_div_fmas_f32 v53, v53, v54, v56
	v_div_fixup_f32 v52, v53, v52, 1.0
	v_pk_mul_f32 v[48:49], v[48:49], v[52:53] op_sel_hi:[1,0]
	v_pk_mul_f32 v[46:47], v[46:47], v[52:53] op_sel_hi:[1,0]
	v_pk_mul_f32 v[44:45], v[44:45], v[52:53] op_sel_hi:[1,0]
	v_pk_mul_f32 v[42:43], v[42:43], v[52:53] op_sel_hi:[1,0]
	v_pk_mul_f32 v[40:41], v[40:41], v[52:53] op_sel_hi:[1,0]
	v_pk_mul_f32 v[38:39], v[38:39], v[52:53] op_sel_hi:[1,0]
	v_pk_mul_f32 v[36:37], v[36:37], v[52:53] op_sel_hi:[1,0]
	v_pk_mul_f32 v[34:35], v[34:35], v[52:53] op_sel_hi:[1,0]
	v_mul_f32_e32 v52, 0xbfb8aa3b, v46
	v_mul_f32_e32 v53, 0xbfb8aa3b, v47
	v_mul_f32_e32 v54, 0xbfb8aa3b, v48
	v_mul_f32_e32 v55, 0xbfb8aa3b, v49
	v_mul_f32_e32 v56, 0xbfb8aa3b, v42
	v_mul_f32_e32 v57, 0xbfb8aa3b, v43
	v_mul_f32_e32 v58, 0xbfb8aa3b, v44
	v_mul_f32_e32 v59, 0xbfb8aa3b, v45
	v_exp_f32_e32 v52, v52
	v_exp_f32_e32 v53, v53
	v_exp_f32_e32 v54, v54
	v_exp_f32_e32 v55, v55
	v_exp_f32_e32 v56, v56
	v_exp_f32_e32 v57, v57
	v_exp_f32_e32 v58, v58
	v_exp_f32_e32 v59, v59
	v_add_f32_e32 v52, 1.0, v52
	v_add_f32_e32 v53, 1.0, v53
	v_add_f32_e32 v54, 1.0, v54
	v_add_f32_e32 v55, 1.0, v55
	v_add_f32_e32 v56, 1.0, v56
	v_add_f32_e32 v57, 1.0, v57
	v_add_f32_e32 v58, 1.0, v58
	v_add_f32_e32 v59, 1.0, v59
	v_rcp_f32_e32 v52, v52
	v_rcp_f32_e32 v53, v53
	v_rcp_f32_e32 v54, v54
	v_rcp_f32_e32 v55, v55
	v_rcp_f32_e32 v56, v56
	v_rcp_f32_e32 v57, v57
	v_rcp_f32_e32 v58, v58
	v_rcp_f32_e32 v59, v59
	v_pk_mul_f32 v[46:47], v[46:47], v[52:53]
	v_pk_mul_f32 v[48:49], v[48:49], v[54:55]
	v_pk_mul_f32 v[42:43], v[42:43], v[56:57]
	v_pk_mul_f32 v[44:45], v[44:45], v[58:59]
	v_pk_mul_f32 v[38:39], v[38:39], v[46:47]
	v_pk_mul_f32 v[40:41], v[40:41], v[48:49]
	v_pk_mul_f32 v[42:43], v[34:35], v[42:43]
	v_pk_mul_f32 v[44:45], v[36:37], v[44:45]
	v_cvt_pk_bf16_f32 v34, v38, v39
	v_cvt_pk_bf16_f32 v35, v40, v41
	v_cvt_pk_bf16_f32 v36, v42, v43
	v_cvt_pk_bf16_f32 v37, v44, v45
	global_store_dwordx4 v[50:51], v[34:37], off
	s_nop 1
	s_nop 0
	v_add_u32_e32 v34, 0xa0, v140
	v_mov_b32_e32 v35, v205
	v_fmamk_f32 v35, v35, 0x39800000, v158
	v_mul_f32_e32 v36, 0x4f800000, v35
	v_cmp_gt_f32_e32 vcc, s57, v35
	s_nop 1
	v_cndmask_b32_e32 v36, v35, v36, vcc
	v_sqrt_f32_e32 v37, v36
	v_mov_b32_e32 v35, v139
	v_lshlrev_b64 v[34:35], 7, v[34:35]
	v_lshl_add_u64 v[34:35], s[22:23], 0, v[34:35]
	v_add_u32_e32 v38, -1, v37
	v_add_u32_e32 v39, 1, v37
	v_fma_f32 v40, -v38, v37, v36
	v_fma_f32 v41, -v39, v37, v36
	v_cmp_ge_f32_e64 s[4:5], 0, v40
	v_lshl_add_u64 v[34:35], v[34:35], 0, v[138:139]
	s_nop 0
	v_cndmask_b32_e64 v37, v37, v38, s[4:5]
	v_cmp_lt_f32_e64 s[4:5], 0, v41
	s_nop 1
	v_cndmask_b32_e64 v37, v37, v39, s[4:5]
	v_mul_f32_e32 v38, 0x37800000, v37
	v_cndmask_b32_e32 v37, v37, v38, vcc
	v_cmp_class_f32_e32 vcc, v36, v159
	s_nop 1
	v_cndmask_b32_e32 v36, v37, v36, vcc
	v_div_scale_f32 v37, s[4:5], v36, v36, 1.0
	v_rcp_f32_e32 v38, v37
	v_div_scale_f32 v39, vcc, 1.0, v36, 1.0
	v_fma_f32 v40, -v37, v38, 1.0
	v_fmac_f32_e32 v38, v40, v38
	v_mul_f32_e32 v40, v39, v38
	v_fma_f32 v41, -v37, v40, v39
	v_fmac_f32_e32 v40, v41, v38
	v_fma_f32 v37, -v37, v40, v39
	v_div_fmas_f32 v37, v37, v38, v40
	v_div_fixup_f32 v36, v37, v36, 1.0
	v_pk_mul_f32 v[32:33], v[32:33], v[36:37] op_sel_hi:[1,0]
	v_pk_mul_f32 v[30:31], v[30:31], v[36:37] op_sel_hi:[1,0]
	v_pk_mul_f32 v[28:29], v[28:29], v[36:37] op_sel_hi:[1,0]
	v_pk_mul_f32 v[26:27], v[26:27], v[36:37] op_sel_hi:[1,0]
; __device__ __forceinline__ float fsilu(float x) { return x * fsigmoid(x); }
; #define PG8_BAR __builtin_amdgcn_s_barrier()
;     __device__ __forceinline__ void operator()(const f32x4 (&acc)[2][2][4][2], const Unit& u, int wr, int wc, int fr, int fq) const {
;     ...
;             for (int m = 0; m < 4; ++m) { const int row = row0 + ai * HALF + m * 16;
;                 bf16_t* rowp = O + (size_t)u.pm * ((size_t)ldc * BM) + (size_t)(col0 >> 6) * (BM * 64) + (size_t)(row - u.pm * BM) * 64 + (col0 & 63);
;                 f32x4 g0 = acc[ai][0][m][0], g1 = acc[ai][0][m][1], u0 = acc[ai][1][m][0], u1 = acc[ai][1][m][1];
;                 if (RS) { const float rs = 1.0f / sqrtf(stat[row] * (1.0f / 4096.0f) + 1e-6f); g0 *= rs; g1 *= rs; u0 *= rs; u1 *= rs; }
;                 u32x4 w; w.x = pk_bf16(fsilu(g0[0]) * u0[0], fsilu(g0[1]) * u0[1]); w.y = pk_bf16(fsilu(g0[2]) * u0[2], fsilu(g0[3]) * u0[3]);
;                 w.z = pk_bf16(fsilu(g1[0]) * u1[0], fsilu(g1[1]) * u1[1]); w.w = pk_bf16(fsilu(g1[2]) * u1[2], fsilu(g1[3]) * u1[3]);
;                 *(u32x4*)rowp = w; }
; template <class Epi, class Sched, bool ALIGN_EPI = false, bool SP2 = false, bool A_TILED = false>
; __device__ __forceinline__ void gemm_phase(PG8_LAS unsigned char* lds, const Gemm g, const Sched& S, const Epi& E) {
;     ...
;         if constexpr (ALIGN_EPI) { if (wr == 0) PG8_BAR; }
;         if constexpr (!Epi::AFTER_DRAIN) { E(acc, cur, wr, wc, fr, fq); S.done(cur); }
;         if (!has_next) break;
; #pragma unroll
;         for (int a = 0; a < 2; ++a)
; #pragma unroll
;             for (int b = 0; b < 2; ++b)
; #pragma unroll
;                 for (int m = 0; m < 4; ++m)
; #pragma unroll
;                     for (int n = 0; n < 2; ++n) acc[a][b][m][n] = (f32x4){0.f, 0.f, 0.f, 0.f};
;         cur = nxt; cA = nA; cB = nB; ++ui;
;         if constexpr (ALIGN_EPI) { if (wr == 1) PG8_BAR; }
	v_pk_mul_f32 v[24:25], v[24:25], v[36:37] op_sel_hi:[1,0]
	v_pk_mul_f32 v[22:23], v[22:23], v[36:37] op_sel_hi:[1,0]
	v_pk_mul_f32 v[20:21], v[20:21], v[36:37] op_sel_hi:[1,0]
	v_pk_mul_f32 v[18:19], v[18:19], v[36:37] op_sel_hi:[1,0]
	v_mul_f32_e32 v36, 0xbfb8aa3b, v30
	v_mul_f32_e32 v37, 0xbfb8aa3b, v31
	v_mul_f32_e32 v38, 0xbfb8aa3b, v32
	v_mul_f32_e32 v39, 0xbfb8aa3b, v33
	v_mul_f32_e32 v40, 0xbfb8aa3b, v26
	v_mul_f32_e32 v41, 0xbfb8aa3b, v27
	v_mul_f32_e32 v42, 0xbfb8aa3b, v28
	v_mul_f32_e32 v43, 0xbfb8aa3b, v29
	v_exp_f32_e32 v36, v36
	v_exp_f32_e32 v37, v37
	v_exp_f32_e32 v38, v38
	v_exp_f32_e32 v39, v39
	v_exp_f32_e32 v40, v40
	v_exp_f32_e32 v41, v41
	v_exp_f32_e32 v42, v42
	v_exp_f32_e32 v43, v43
	v_add_f32_e32 v36, 1.0, v36
	v_add_f32_e32 v37, 1.0, v37
	v_add_f32_e32 v38, 1.0, v38
	v_add_f32_e32 v39, 1.0, v39
	v_add_f32_e32 v40, 1.0, v40
	v_add_f32_e32 v41, 1.0, v41
	v_add_f32_e32 v42, 1.0, v42
	v_add_f32_e32 v43, 1.0, v43
	v_rcp_f32_e32 v36, v36
	v_rcp_f32_e32 v37, v37
	v_rcp_f32_e32 v38, v38
	v_rcp_f32_e32 v39, v39
	v_rcp_f32_e32 v40, v40
	v_rcp_f32_e32 v41, v41
	v_rcp_f32_e32 v42, v42
	v_rcp_f32_e32 v43, v43
	v_pk_mul_f32 v[30:31], v[30:31], v[36:37]
	v_pk_mul_f32 v[32:33], v[32:33], v[38:39]
	v_pk_mul_f32 v[26:27], v[26:27], v[40:41]
	v_pk_mul_f32 v[28:29], v[28:29], v[42:43]
	v_pk_mul_f32 v[22:23], v[22:23], v[30:31]
	v_pk_mul_f32 v[24:25], v[24:25], v[32:33]
	v_pk_mul_f32 v[26:27], v[18:19], v[26:27]
	v_pk_mul_f32 v[28:29], v[20:21], v[28:29]
	v_cvt_pk_bf16_f32 v18, v22, v23
	v_cvt_pk_bf16_f32 v19, v24, v25
	v_cvt_pk_bf16_f32 v20, v26, v27
	v_cvt_pk_bf16_f32 v21, v28, v29
	global_store_dwordx4 v[34:35], v[18:21], off
	s_nop 1
	s_nop 0
	v_add_u32_e32 v18, 0xb0, v140
	v_mov_b32_e32 v19, v139
	v_lshlrev_b64 v[18:19], 7, v[18:19]
	v_lshl_add_u64 v[18:19], s[22:23], 0, v[18:19]
	v_lshl_add_u64 v[18:19], v[18:19], 0, v[138:139]
	v_mov_b32_e32 v20, v206
	v_fmamk_f32 v20, v20, 0x39800000, v158
	v_mul_f32_e32 v21, 0x4f800000, v20
	v_cmp_gt_f32_e32 vcc, s57, v20
	s_nop 1
	v_cndmask_b32_e32 v20, v20, v21, vcc
	v_sqrt_f32_e32 v21, v20
	s_nop 0
	v_add_u32_e32 v22, -1, v21
	v_add_u32_e32 v23, 1, v21
	v_fma_f32 v24, -v22, v21, v20
	v_fma_f32 v25, -v23, v21, v20
	v_cmp_ge_f32_e64 s[4:5], 0, v24
	s_nop 1
	v_cndmask_b32_e64 v21, v21, v22, s[4:5]
	v_cmp_lt_f32_e64 s[4:5], 0, v25
	s_nop 1
	v_cndmask_b32_e64 v21, v21, v23, s[4:5]
	v_mul_f32_e32 v22, 0x37800000, v21
	v_cndmask_b32_e32 v21, v21, v22, vcc
	v_cmp_class_f32_e32 vcc, v20, v159
	s_nop 1
	v_cndmask_b32_e32 v20, v21, v20, vcc
	v_div_scale_f32 v21, s[4:5], v20, v20, 1.0
	v_rcp_f32_e32 v22, v21
	v_div_scale_f32 v23, vcc, 1.0, v20, 1.0
	v_fma_f32 v24, -v21, v22, 1.0
	v_fmac_f32_e32 v22, v24, v22
	v_mul_f32_e32 v24, v23, v22
	v_fma_f32 v25, -v21, v24, v23
	v_fmac_f32_e32 v24, v25, v22
	v_fma_f32 v21, -v21, v24, v23
	v_div_fmas_f32 v21, v21, v22, v24
	v_div_fixup_f32 v20, v21, v20, 1.0
	v_pk_mul_f32 v[16:17], v[16:17], v[20:21] op_sel_hi:[1,0]
	v_pk_mul_f32 v[14:15], v[14:15], v[20:21] op_sel_hi:[1,0]
	v_pk_mul_f32 v[12:13], v[12:13], v[20:21] op_sel_hi:[1,0]
	v_pk_mul_f32 v[10:11], v[10:11], v[20:21] op_sel_hi:[1,0]
	v_pk_mul_f32 v[8:9], v[8:9], v[20:21] op_sel_hi:[1,0]
	v_pk_mul_f32 v[6:7], v[6:7], v[20:21] op_sel_hi:[1,0]
	v_pk_mul_f32 v[4:5], v[4:5], v[20:21] op_sel_hi:[1,0]
	v_pk_mul_f32 v[2:3], v[2:3], v[20:21] op_sel_hi:[1,0]
	v_mul_f32_e32 v20, 0xbfb8aa3b, v14
	v_mul_f32_e32 v21, 0xbfb8aa3b, v15
	v_mul_f32_e32 v22, 0xbfb8aa3b, v16
	v_mul_f32_e32 v23, 0xbfb8aa3b, v17
	v_mul_f32_e32 v24, 0xbfb8aa3b, v10
	v_mul_f32_e32 v25, 0xbfb8aa3b, v11
	v_mul_f32_e32 v26, 0xbfb8aa3b, v12
	v_mul_f32_e32 v27, 0xbfb8aa3b, v13
	v_exp_f32_e32 v20, v20
	v_exp_f32_e32 v21, v21
	v_exp_f32_e32 v22, v22
	v_exp_f32_e32 v23, v23
	v_exp_f32_e32 v24, v24
	v_exp_f32_e32 v25, v25
	v_exp_f32_e32 v26, v26
	v_exp_f32_e32 v27, v27
	v_add_f32_e32 v20, 1.0, v20
	v_add_f32_e32 v21, 1.0, v21
	v_add_f32_e32 v22, 1.0, v22
	v_add_f32_e32 v23, 1.0, v23
	v_add_f32_e32 v24, 1.0, v24
	v_add_f32_e32 v25, 1.0, v25
	v_add_f32_e32 v26, 1.0, v26
	v_add_f32_e32 v27, 1.0, v27
	v_rcp_f32_e32 v20, v20
	v_rcp_f32_e32 v21, v21
	v_rcp_f32_e32 v22, v22
	v_rcp_f32_e32 v23, v23
	v_rcp_f32_e32 v24, v24
	v_rcp_f32_e32 v25, v25
	v_rcp_f32_e32 v26, v26
	v_rcp_f32_e32 v27, v27
	v_pk_mul_f32 v[14:15], v[14:15], v[20:21]
	v_pk_mul_f32 v[16:17], v[16:17], v[22:23]
	v_pk_mul_f32 v[10:11], v[10:11], v[24:25]
	v_pk_mul_f32 v[12:13], v[12:13], v[26:27]
	v_pk_mul_f32 v[6:7], v[6:7], v[14:15]
	v_pk_mul_f32 v[8:9], v[8:9], v[16:17]
	v_pk_mul_f32 v[10:11], v[2:3], v[10:11]
	v_pk_mul_f32 v[12:13], v[4:5], v[12:13]
	s_andn2_b64 vcc, exec, s[0:1]
	v_cvt_pk_bf16_f32 v2, v6, v7
	v_cvt_pk_bf16_f32 v3, v8, v9
	v_cvt_pk_bf16_f32 v4, v10, v11
	v_cvt_pk_bf16_f32 v5, v12, v13
	s_mov_b64 s[0:1], -1
	global_store_dwordx4 v[18:19], v[2:5], off
	s_cbranch_vccnz .LBB0_1168
	s_andn2_b64 vcc, exec, s[10:11]
	s_cbranch_vccnz .LBB0_1167
	s_barrier
	s_branch .LBB0_1167
